# adaLN GEMV: 32 row loads in flight per trip instead of 4; attention K/V staging: counted vmcnt(4) instead of the compiler 3..0 ladder
# speedup vs baseline: 1.0062x; 1.0062x over previous
; #define LAS __attribute__((address_space(3)))
; DI void prep_phase(const Args& A, LAS unsigned char* lds, int wv) {
;     ...
;             float acc[17];
; #pragma unroll
;             for (int r = 0; r < 17; ++r) acc[r] = 0.f;
;             const float* wp = aw + ((size_t)l * DM + k0) * MOD_LD + j;
; #pragma unroll 4
;             for (int k = 0; k < 128; ++k) {
;                 const float w = wp[(size_t)k * MOD_LD];
;                 const LAS f32x4* sp = (const LAS f32x4*)(s_lds + k * 20);
;                 const f32x4 s0 = sp[0], s1 = sp[1], s2 = sp[2], s3 = sp[3]; const float s4 = s_lds[k * 20 + 16];
.LBB0_11:
	s_or_b64 exec, exec, s[8:9]
	s_ashr_i32 s4, s41, 4
	s_mul_hi_i32 s5, s4, 0x2aaaaaab
	s_lshr_b32 s8, s5, 31
	s_lshr_b32 s5, s5, 1
	s_add_i32 s5, s5, s8
	s_mul_i32 s5, s5, 12
	s_sub_i32 s4, s4, s5
	s_mul_hi_i32 s5, s38, 0x2aaaaaab
	s_lshr_b32 s8, s5, 31
	s_ashr_i32 s5, s5, 5
	s_add_i32 s8, s5, s8
	s_ashr_i32 s9, s8, 31
	v_lshl_add_u32 v16, s4, 9, v2
	s_lshl_b64 s[4:5], s[8:9], 11
	s_ashr_i32 s9, s40, 31
	s_add_u32 s4, s4, s40
	s_addc_u32 s5, s5, s9
	s_mulk_i32 s5, 0x6000
	s_mul_hi_u32 s9, s4, 0x6000
	s_add_i32 s9, s9, s5
	s_mulk_i32 s4, 0x6000
	s_add_u32 s4, s20, s4
	s_addc_u32 s5, s21, s9
	v_ashrrev_i32_e32 v17, 31, v16
	v_mov_b32_e32 v20, 0
	v_lshl_add_u64 v[22:23], v[16:17], 2, s[4:5]
	s_mov_b64 s[10:11], 0
	s_mov_b32 s9, 0
	v_mov_b32_e32 v21, v20
	v_mov_b32_e32 v18, v20
	v_mov_b32_e32 v19, v20
	v_mov_b32_e32 v14, v20
	v_mov_b32_e32 v15, v20
	v_mov_b32_e32 v12, v20
	v_mov_b32_e32 v13, v20
	v_mov_b32_e32 v10, v20
	v_mov_b32_e32 v11, v20
	v_mov_b32_e32 v8, v20
	v_mov_b32_e32 v9, v20
	v_mov_b32_e32 v6, v20
	v_mov_b32_e32 v7, v20
	v_mov_b32_e32 v4, v20
	v_mov_b32_e32 v5, v20
	v_mov_b32_e32 v25, v20
	s_waitcnt lgkmcnt(0)
	s_barrier
	s_mov_b32 s100, 0x6000
	s_mov_b32 s101, 0
.LBB0_12:
	v_lshl_add_u64 v[26:27], v[22:23], 0, s[10:11]
	global_load_dword v102, v[26:27], off
	v_lshl_add_u64 v[26:27], v[26:27], 0, s[100:101]
	global_load_dword v104, v[26:27], off
	v_lshl_add_u64 v[26:27], v[26:27], 0, s[100:101]
	global_load_dword v106, v[26:27], off
	v_lshl_add_u64 v[26:27], v[26:27], 0, s[100:101]
	global_load_dword v108, v[26:27], off
	v_lshl_add_u64 v[26:27], v[26:27], 0, s[100:101]
	global_load_dword v110, v[26:27], off
	v_lshl_add_u64 v[26:27], v[26:27], 0, s[100:101]
	global_load_dword v112, v[26:27], off
	v_lshl_add_u64 v[26:27], v[26:27], 0, s[100:101]
	global_load_dword v114, v[26:27], off
	v_lshl_add_u64 v[26:27], v[26:27], 0, s[100:101]
	global_load_dword v116, v[26:27], off
	v_lshl_add_u64 v[26:27], v[26:27], 0, s[100:101]
	global_load_dword v118, v[26:27], off
	v_lshl_add_u64 v[26:27], v[26:27], 0, s[100:101]
	global_load_dword v120, v[26:27], off
	v_lshl_add_u64 v[26:27], v[26:27], 0, s[100:101]
	global_load_dword v122, v[26:27], off
	v_lshl_add_u64 v[26:27], v[26:27], 0, s[100:101]
	global_load_dword v124, v[26:27], off
	v_lshl_add_u64 v[26:27], v[26:27], 0, s[100:101]
	global_load_dword v126, v[26:27], off
	v_lshl_add_u64 v[26:27], v[26:27], 0, s[100:101]
	global_load_dword v128, v[26:27], off
	v_lshl_add_u64 v[26:27], v[26:27], 0, s[100:101]
	global_load_dword v130, v[26:27], off
	v_lshl_add_u64 v[26:27], v[26:27], 0, s[100:101]
	global_load_dword v132, v[26:27], off
	v_lshl_add_u64 v[26:27], v[26:27], 0, s[100:101]
	global_load_dword v134, v[26:27], off
	v_lshl_add_u64 v[26:27], v[26:27], 0, s[100:101]
	global_load_dword v136, v[26:27], off
	v_lshl_add_u64 v[26:27], v[26:27], 0, s[100:101]
	global_load_dword v138, v[26:27], off
	v_lshl_add_u64 v[26:27], v[26:27], 0, s[100:101]
	global_load_dword v140, v[26:27], off
	v_lshl_add_u64 v[26:27], v[26:27], 0, s[100:101]
	global_load_dword v142, v[26:27], off
	v_lshl_add_u64 v[26:27], v[26:27], 0, s[100:101]
	global_load_dword v144, v[26:27], off
	v_lshl_add_u64 v[26:27], v[26:27], 0, s[100:101]
	global_load_dword v146, v[26:27], off
	v_lshl_add_u64 v[26:27], v[26:27], 0, s[100:101]
	global_load_dword v148, v[26:27], off
	v_lshl_add_u64 v[26:27], v[26:27], 0, s[100:101]
	global_load_dword v150, v[26:27], off
	v_lshl_add_u64 v[26:27], v[26:27], 0, s[100:101]
	global_load_dword v152, v[26:27], off
	v_lshl_add_u64 v[26:27], v[26:27], 0, s[100:101]
	global_load_dword v154, v[26:27], off
	v_lshl_add_u64 v[26:27], v[26:27], 0, s[100:101]
	global_load_dword v156, v[26:27], off
	v_lshl_add_u64 v[26:27], v[26:27], 0, s[100:101]
	global_load_dword v158, v[26:27], off
	v_lshl_add_u64 v[26:27], v[26:27], 0, s[100:101]
	global_load_dword v160, v[26:27], off
	v_lshl_add_u64 v[26:27], v[26:27], 0, s[100:101]
	global_load_dword v162, v[26:27], off
	v_lshl_add_u64 v[26:27], v[26:27], 0, s[100:101]
	global_load_dword v164, v[26:27], off
	v_mov_b32_e32 v166, s9
	v_add_u32_e32 v167, 0x140, v166
	v_add_u32_e32 v168, 0x140, v167
	v_add_u32_e32 v169, 0x140, v168
	v_add_u32_e32 v170, 0x140, v169
	v_add_u32_e32 v171, 0x140, v170
	v_add_u32_e32 v172, 0x140, v171
	v_add_u32_e32 v173, 0x140, v172
	ds_read_b128 v[26:29], v166
	ds_read_b128 v[34:37], v166 offset:16
	ds_read_b128 v[38:41], v166 offset:32
	ds_read_b128 v[42:45], v166 offset:48
	ds_read2_b32 v[98:99], v166 offset0:16 offset1:36
	ds_read_b128 v[46:49], v166 offset:80
	ds_read_b128 v[50:53], v166 offset:96
	ds_read_b128 v[54:57], v166 offset:112
	ds_read_b128 v[58:61], v166 offset:128
	ds_read_b128 v[62:65], v166 offset:160
	ds_read_b128 v[66:69], v166 offset:176
	ds_read_b128 v[70:73], v166 offset:192
	ds_read_b128 v[74:77], v166 offset:208
	ds_read2_b32 v[100:101], v166 offset0:56 offset1:76
	ds_read_b128 v[78:81], v166 offset:240
	ds_read_b128 v[82:85], v166 offset:256
	ds_read_b128 v[86:89], v166 offset:272
	ds_read_b128 v[90:93], v166 offset:288
	s_waitcnt vmcnt(31) lgkmcnt(14)
	v_pk_fma_f32 v[20:21], v[102:103], v[26:27], v[20:21] op_sel_hi:[0,1,1]
	v_pk_fma_f32 v[18:19], v[102:103], v[28:29], v[18:19] op_sel_hi:[0,1,1]
	v_pk_fma_f32 v[14:15], v[102:103], v[34:35], v[14:15] op_sel_hi:[0,1,1]
	v_pk_fma_f32 v[12:13], v[102:103], v[36:37], v[12:13] op_sel_hi:[0,1,1]
	v_pk_fma_f32 v[10:11], v[102:103], v[38:39], v[10:11] op_sel_hi:[0,1,1]
	v_pk_fma_f32 v[8:9], v[102:103], v[40:41], v[8:9] op_sel_hi:[0,1,1]
	v_pk_fma_f32 v[6:7], v[102:103], v[42:43], v[6:7] op_sel_hi:[0,1,1]
	v_pk_fma_f32 v[4:5], v[102:103], v[44:45], v[4:5] op_sel_hi:[0,1,1]
	s_waitcnt lgkmcnt(13)
; #define LAS __attribute__((address_space(3)))
; DI void prep_phase(const Args& A, LAS unsigned char* lds, int wv) {
;     ...
;             for (int k = 0; k < 128; ++k) {
;                 const float w = wp[(size_t)k * MOD_LD];
;                 const LAS f32x4* sp = (const LAS f32x4*)(s_lds + k * 20);
;                 const f32x4 s0 = sp[0], s1 = sp[1], s2 = sp[2], s3 = sp[3]; const float s4 = s_lds[k * 20 + 16];
; #pragma unroll
;                 for (int q = 0; q < 4; ++q) { acc[q] += s0[q] * w; acc[4 + q] += s1[q] * w; acc[8 + q] += s2[q] * w; acc[12 + q] += s3[q] * w; }
;                 acc[16] += s4 * w;
	v_fmac_f32_e32 v25, v102, v98
	s_waitcnt vmcnt(30) lgkmcnt(12)
	v_pk_fma_f32 v[20:21], v[104:105], v[46:47], v[20:21] op_sel_hi:[0,1,1]
	v_pk_fma_f32 v[18:19], v[104:105], v[48:49], v[18:19] op_sel_hi:[0,1,1]
	s_waitcnt lgkmcnt(11)
	v_pk_fma_f32 v[14:15], v[104:105], v[50:51], v[14:15] op_sel_hi:[0,1,1]
	v_pk_fma_f32 v[12:13], v[104:105], v[52:53], v[12:13] op_sel_hi:[0,1,1]
	s_waitcnt lgkmcnt(10)
	v_pk_fma_f32 v[10:11], v[104:105], v[54:55], v[10:11] op_sel_hi:[0,1,1]
	v_pk_fma_f32 v[8:9], v[104:105], v[56:57], v[8:9] op_sel_hi:[0,1,1]
	s_waitcnt lgkmcnt(9)
	v_pk_fma_f32 v[6:7], v[104:105], v[58:59], v[6:7] op_sel_hi:[0,1,1]
	v_pk_fma_f32 v[4:5], v[104:105], v[60:61], v[4:5] op_sel_hi:[0,1,1]
	v_fmac_f32_e32 v25, v104, v99
	s_waitcnt vmcnt(29) lgkmcnt(8)
	v_pk_fma_f32 v[20:21], v[106:107], v[62:63], v[20:21] op_sel_hi:[0,1,1]
	s_waitcnt lgkmcnt(7)
	v_pk_fma_f32 v[14:15], v[106:107], v[66:67], v[14:15] op_sel_hi:[0,1,1]
	s_waitcnt lgkmcnt(6)
	v_pk_fma_f32 v[10:11], v[106:107], v[70:71], v[10:11] op_sel_hi:[0,1,1]
	s_waitcnt lgkmcnt(5)
	v_pk_fma_f32 v[6:7], v[106:107], v[74:75], v[6:7] op_sel_hi:[0,1,1]
	v_pk_fma_f32 v[18:19], v[106:107], v[64:65], v[18:19] op_sel_hi:[0,1,1]
	v_pk_fma_f32 v[12:13], v[106:107], v[68:69], v[12:13] op_sel_hi:[0,1,1]
	v_pk_fma_f32 v[8:9], v[106:107], v[72:73], v[8:9] op_sel_hi:[0,1,1]
	v_pk_fma_f32 v[4:5], v[106:107], v[76:77], v[4:5] op_sel_hi:[0,1,1]
	s_waitcnt lgkmcnt(4)
	v_fmac_f32_e32 v25, v106, v100
	s_waitcnt vmcnt(28) lgkmcnt(3)
	v_pk_fma_f32 v[20:21], v[108:109], v[78:79], v[20:21] op_sel_hi:[0,1,1]
	s_waitcnt lgkmcnt(2)
	v_pk_fma_f32 v[14:15], v[108:109], v[82:83], v[14:15] op_sel_hi:[0,1,1]
	s_waitcnt lgkmcnt(1)
	v_pk_fma_f32 v[10:11], v[108:109], v[86:87], v[10:11] op_sel_hi:[0,1,1]
	s_waitcnt lgkmcnt(0)
	v_pk_fma_f32 v[6:7], v[108:109], v[90:91], v[6:7] op_sel_hi:[0,1,1]
	v_pk_fma_f32 v[18:19], v[108:109], v[80:81], v[18:19] op_sel_hi:[0,1,1]
	v_pk_fma_f32 v[12:13], v[108:109], v[84:85], v[12:13] op_sel_hi:[0,1,1]
	v_pk_fma_f32 v[8:9], v[108:109], v[88:89], v[8:9] op_sel_hi:[0,1,1]
	v_pk_fma_f32 v[4:5], v[108:109], v[92:93], v[4:5] op_sel_hi:[0,1,1]
	v_fmac_f32_e32 v25, v108, v101
	ds_read_b128 v[26:29], v167
	ds_read_b128 v[34:37], v167 offset:16
	ds_read_b128 v[38:41], v167 offset:32
	ds_read_b128 v[42:45], v167 offset:48
	ds_read2_b32 v[98:99], v167 offset0:16 offset1:36
	ds_read_b128 v[46:49], v167 offset:80
	ds_read_b128 v[50:53], v167 offset:96
	ds_read_b128 v[54:57], v167 offset:112
	ds_read_b128 v[58:61], v167 offset:128
	ds_read_b128 v[62:65], v167 offset:160
	ds_read_b128 v[66:69], v167 offset:176
	ds_read_b128 v[70:73], v167 offset:192
	ds_read_b128 v[74:77], v167 offset:208
	ds_read2_b32 v[100:101], v167 offset0:56 offset1:76
	ds_read_b128 v[78:81], v167 offset:240
	ds_read_b128 v[82:85], v167 offset:256
	ds_read_b128 v[86:89], v167 offset:272
	ds_read_b128 v[90:93], v167 offset:288
	s_waitcnt vmcnt(27) lgkmcnt(14)
	v_pk_fma_f32 v[20:21], v[110:111], v[26:27], v[20:21] op_sel_hi:[0,1,1]
	v_pk_fma_f32 v[18:19], v[110:111], v[28:29], v[18:19] op_sel_hi:[0,1,1]
	v_pk_fma_f32 v[14:15], v[110:111], v[34:35], v[14:15] op_sel_hi:[0,1,1]
	v_pk_fma_f32 v[12:13], v[110:111], v[36:37], v[12:13] op_sel_hi:[0,1,1]
	v_pk_fma_f32 v[10:11], v[110:111], v[38:39], v[10:11] op_sel_hi:[0,1,1]
	v_pk_fma_f32 v[8:9], v[110:111], v[40:41], v[8:9] op_sel_hi:[0,1,1]
	v_pk_fma_f32 v[6:7], v[110:111], v[42:43], v[6:7] op_sel_hi:[0,1,1]
	v_pk_fma_f32 v[4:5], v[110:111], v[44:45], v[4:5] op_sel_hi:[0,1,1]
	s_waitcnt lgkmcnt(13)
	v_fmac_f32_e32 v25, v110, v98
	s_waitcnt vmcnt(26) lgkmcnt(12)
	v_pk_fma_f32 v[20:21], v[112:113], v[46:47], v[20:21] op_sel_hi:[0,1,1]
	v_pk_fma_f32 v[18:19], v[112:113], v[48:49], v[18:19] op_sel_hi:[0,1,1]
	s_waitcnt lgkmcnt(11)
	v_pk_fma_f32 v[14:15], v[112:113], v[50:51], v[14:15] op_sel_hi:[0,1,1]
	v_pk_fma_f32 v[12:13], v[112:113], v[52:53], v[12:13] op_sel_hi:[0,1,1]
	s_waitcnt lgkmcnt(10)
	v_pk_fma_f32 v[10:11], v[112:113], v[54:55], v[10:11] op_sel_hi:[0,1,1]
	v_pk_fma_f32 v[8:9], v[112:113], v[56:57], v[8:9] op_sel_hi:[0,1,1]
	s_waitcnt lgkmcnt(9)
	v_pk_fma_f32 v[6:7], v[112:113], v[58:59], v[6:7] op_sel_hi:[0,1,1]
	v_pk_fma_f32 v[4:5], v[112:113], v[60:61], v[4:5] op_sel_hi:[0,1,1]
	v_fmac_f32_e32 v25, v112, v99
	s_waitcnt vmcnt(25) lgkmcnt(8)
	v_pk_fma_f32 v[20:21], v[114:115], v[62:63], v[20:21] op_sel_hi:[0,1,1]
	s_waitcnt lgkmcnt(7)
	v_pk_fma_f32 v[14:15], v[114:115], v[66:67], v[14:15] op_sel_hi:[0,1,1]
	s_waitcnt lgkmcnt(6)
	v_pk_fma_f32 v[10:11], v[114:115], v[70:71], v[10:11] op_sel_hi:[0,1,1]
	s_waitcnt lgkmcnt(5)
	v_pk_fma_f32 v[6:7], v[114:115], v[74:75], v[6:7] op_sel_hi:[0,1,1]
	v_pk_fma_f32 v[18:19], v[114:115], v[64:65], v[18:19] op_sel_hi:[0,1,1]
	v_pk_fma_f32 v[12:13], v[114:115], v[68:69], v[12:13] op_sel_hi:[0,1,1]
	v_pk_fma_f32 v[8:9], v[114:115], v[72:73], v[8:9] op_sel_hi:[0,1,1]
	v_pk_fma_f32 v[4:5], v[114:115], v[76:77], v[4:5] op_sel_hi:[0,1,1]
	s_waitcnt lgkmcnt(4)
	v_fmac_f32_e32 v25, v114, v100
	s_waitcnt vmcnt(24) lgkmcnt(3)
	v_pk_fma_f32 v[20:21], v[116:117], v[78:79], v[20:21] op_sel_hi:[0,1,1]
	s_waitcnt lgkmcnt(2)
	v_pk_fma_f32 v[14:15], v[116:117], v[82:83], v[14:15] op_sel_hi:[0,1,1]
	s_waitcnt lgkmcnt(1)
	v_pk_fma_f32 v[10:11], v[116:117], v[86:87], v[10:11] op_sel_hi:[0,1,1]
	s_waitcnt lgkmcnt(0)
; #define LAS __attribute__((address_space(3)))
; DI void prep_phase(const Args& A, LAS unsigned char* lds, int wv) {
;     ...
;             for (int k = 0; k < 128; ++k) {
;                 const float w = wp[(size_t)k * MOD_LD];
;                 const LAS f32x4* sp = (const LAS f32x4*)(s_lds + k * 20);
;                 const f32x4 s0 = sp[0], s1 = sp[1], s2 = sp[2], s3 = sp[3]; const float s4 = s_lds[k * 20 + 16];
; #pragma unroll
;                 for (int q = 0; q < 4; ++q) { acc[q] += s0[q] * w; acc[4 + q] += s1[q] * w; acc[8 + q] += s2[q] * w; acc[12 + q] += s3[q] * w; }
;                 acc[16] += s4 * w;
	v_pk_fma_f32 v[6:7], v[116:117], v[90:91], v[6:7] op_sel_hi:[0,1,1]
	v_pk_fma_f32 v[18:19], v[116:117], v[80:81], v[18:19] op_sel_hi:[0,1,1]
	v_pk_fma_f32 v[12:13], v[116:117], v[84:85], v[12:13] op_sel_hi:[0,1,1]
	v_pk_fma_f32 v[8:9], v[116:117], v[88:89], v[8:9] op_sel_hi:[0,1,1]
	v_pk_fma_f32 v[4:5], v[116:117], v[92:93], v[4:5] op_sel_hi:[0,1,1]
	v_fmac_f32_e32 v25, v116, v101
	ds_read_b128 v[26:29], v168
	ds_read_b128 v[34:37], v168 offset:16
	ds_read_b128 v[38:41], v168 offset:32
	ds_read_b128 v[42:45], v168 offset:48
	ds_read2_b32 v[98:99], v168 offset0:16 offset1:36
	ds_read_b128 v[46:49], v168 offset:80
	ds_read_b128 v[50:53], v168 offset:96
	ds_read_b128 v[54:57], v168 offset:112
	ds_read_b128 v[58:61], v168 offset:128
	ds_read_b128 v[62:65], v168 offset:160
	ds_read_b128 v[66:69], v168 offset:176
	ds_read_b128 v[70:73], v168 offset:192
	ds_read_b128 v[74:77], v168 offset:208
	ds_read2_b32 v[100:101], v168 offset0:56 offset1:76
	ds_read_b128 v[78:81], v168 offset:240
	ds_read_b128 v[82:85], v168 offset:256
	ds_read_b128 v[86:89], v168 offset:272
	ds_read_b128 v[90:93], v168 offset:288
	s_waitcnt vmcnt(23) lgkmcnt(14)
	v_pk_fma_f32 v[20:21], v[118:119], v[26:27], v[20:21] op_sel_hi:[0,1,1]
	v_pk_fma_f32 v[18:19], v[118:119], v[28:29], v[18:19] op_sel_hi:[0,1,1]
	v_pk_fma_f32 v[14:15], v[118:119], v[34:35], v[14:15] op_sel_hi:[0,1,1]
	v_pk_fma_f32 v[12:13], v[118:119], v[36:37], v[12:13] op_sel_hi:[0,1,1]
	v_pk_fma_f32 v[10:11], v[118:119], v[38:39], v[10:11] op_sel_hi:[0,1,1]
	v_pk_fma_f32 v[8:9], v[118:119], v[40:41], v[8:9] op_sel_hi:[0,1,1]
	v_pk_fma_f32 v[6:7], v[118:119], v[42:43], v[6:7] op_sel_hi:[0,1,1]
	v_pk_fma_f32 v[4:5], v[118:119], v[44:45], v[4:5] op_sel_hi:[0,1,1]
	s_waitcnt lgkmcnt(13)
	v_fmac_f32_e32 v25, v118, v98
	s_waitcnt vmcnt(22) lgkmcnt(12)
	v_pk_fma_f32 v[20:21], v[120:121], v[46:47], v[20:21] op_sel_hi:[0,1,1]
	v_pk_fma_f32 v[18:19], v[120:121], v[48:49], v[18:19] op_sel_hi:[0,1,1]
	s_waitcnt lgkmcnt(11)
	v_pk_fma_f32 v[14:15], v[120:121], v[50:51], v[14:15] op_sel_hi:[0,1,1]
	v_pk_fma_f32 v[12:13], v[120:121], v[52:53], v[12:13] op_sel_hi:[0,1,1]
	s_waitcnt lgkmcnt(10)
	v_pk_fma_f32 v[10:11], v[120:121], v[54:55], v[10:11] op_sel_hi:[0,1,1]
	v_pk_fma_f32 v[8:9], v[120:121], v[56:57], v[8:9] op_sel_hi:[0,1,1]
	s_waitcnt lgkmcnt(9)
	v_pk_fma_f32 v[6:7], v[120:121], v[58:59], v[6:7] op_sel_hi:[0,1,1]
	v_pk_fma_f32 v[4:5], v[120:121], v[60:61], v[4:5] op_sel_hi:[0,1,1]
	v_fmac_f32_e32 v25, v120, v99
	s_waitcnt vmcnt(21) lgkmcnt(8)
	v_pk_fma_f32 v[20:21], v[122:123], v[62:63], v[20:21] op_sel_hi:[0,1,1]
	s_waitcnt lgkmcnt(7)
	v_pk_fma_f32 v[14:15], v[122:123], v[66:67], v[14:15] op_sel_hi:[0,1,1]
	s_waitcnt lgkmcnt(6)
	v_pk_fma_f32 v[10:11], v[122:123], v[70:71], v[10:11] op_sel_hi:[0,1,1]
	s_waitcnt lgkmcnt(5)
	v_pk_fma_f32 v[6:7], v[122:123], v[74:75], v[6:7] op_sel_hi:[0,1,1]
	v_pk_fma_f32 v[18:19], v[122:123], v[64:65], v[18:19] op_sel_hi:[0,1,1]
	v_pk_fma_f32 v[12:13], v[122:123], v[68:69], v[12:13] op_sel_hi:[0,1,1]
	v_pk_fma_f32 v[8:9], v[122:123], v[72:73], v[8:9] op_sel_hi:[0,1,1]
	v_pk_fma_f32 v[4:5], v[122:123], v[76:77], v[4:5] op_sel_hi:[0,1,1]
	s_waitcnt lgkmcnt(4)
	v_fmac_f32_e32 v25, v122, v100
	s_waitcnt vmcnt(20) lgkmcnt(3)
	v_pk_fma_f32 v[20:21], v[124:125], v[78:79], v[20:21] op_sel_hi:[0,1,1]
	s_waitcnt lgkmcnt(2)
	v_pk_fma_f32 v[14:15], v[124:125], v[82:83], v[14:15] op_sel_hi:[0,1,1]
	s_waitcnt lgkmcnt(1)
	v_pk_fma_f32 v[10:11], v[124:125], v[86:87], v[10:11] op_sel_hi:[0,1,1]
	s_waitcnt lgkmcnt(0)
	v_pk_fma_f32 v[6:7], v[124:125], v[90:91], v[6:7] op_sel_hi:[0,1,1]
	v_pk_fma_f32 v[18:19], v[124:125], v[80:81], v[18:19] op_sel_hi:[0,1,1]
	v_pk_fma_f32 v[12:13], v[124:125], v[84:85], v[12:13] op_sel_hi:[0,1,1]
	v_pk_fma_f32 v[8:9], v[124:125], v[88:89], v[8:9] op_sel_hi:[0,1,1]
	v_pk_fma_f32 v[4:5], v[124:125], v[92:93], v[4:5] op_sel_hi:[0,1,1]
	v_fmac_f32_e32 v25, v124, v101
	ds_read_b128 v[26:29], v169
	ds_read_b128 v[34:37], v169 offset:16
	ds_read_b128 v[38:41], v169 offset:32
	ds_read_b128 v[42:45], v169 offset:48
	ds_read2_b32 v[98:99], v169 offset0:16 offset1:36
	ds_read_b128 v[46:49], v169 offset:80
	ds_read_b128 v[50:53], v169 offset:96
	ds_read_b128 v[54:57], v169 offset:112
	ds_read_b128 v[58:61], v169 offset:128
	ds_read_b128 v[62:65], v169 offset:160
	ds_read_b128 v[66:69], v169 offset:176
	ds_read_b128 v[70:73], v169 offset:192
	ds_read_b128 v[74:77], v169 offset:208
	ds_read2_b32 v[100:101], v169 offset0:56 offset1:76
	ds_read_b128 v[78:81], v169 offset:240
	ds_read_b128 v[82:85], v169 offset:256
	ds_read_b128 v[86:89], v169 offset:272
	ds_read_b128 v[90:93], v169 offset:288
	s_waitcnt vmcnt(19) lgkmcnt(14)
	v_pk_fma_f32 v[20:21], v[126:127], v[26:27], v[20:21] op_sel_hi:[0,1,1]
	v_pk_fma_f32 v[18:19], v[126:127], v[28:29], v[18:19] op_sel_hi:[0,1,1]
	v_pk_fma_f32 v[14:15], v[126:127], v[34:35], v[14:15] op_sel_hi:[0,1,1]
	v_pk_fma_f32 v[12:13], v[126:127], v[36:37], v[12:13] op_sel_hi:[0,1,1]
	v_pk_fma_f32 v[10:11], v[126:127], v[38:39], v[10:11] op_sel_hi:[0,1,1]
	v_pk_fma_f32 v[8:9], v[126:127], v[40:41], v[8:9] op_sel_hi:[0,1,1]
	v_pk_fma_f32 v[6:7], v[126:127], v[42:43], v[6:7] op_sel_hi:[0,1,1]
	v_pk_fma_f32 v[4:5], v[126:127], v[44:45], v[4:5] op_sel_hi:[0,1,1]
	s_waitcnt lgkmcnt(13)
	v_fmac_f32_e32 v25, v126, v98
	s_waitcnt vmcnt(18) lgkmcnt(12)
	v_pk_fma_f32 v[20:21], v[128:129], v[46:47], v[20:21] op_sel_hi:[0,1,1]
	v_pk_fma_f32 v[18:19], v[128:129], v[48:49], v[18:19] op_sel_hi:[0,1,1]
	s_waitcnt lgkmcnt(11)
	v_pk_fma_f32 v[14:15], v[128:129], v[50:51], v[14:15] op_sel_hi:[0,1,1]
	v_pk_fma_f32 v[12:13], v[128:129], v[52:53], v[12:13] op_sel_hi:[0,1,1]
	s_waitcnt lgkmcnt(10)
; #define LAS __attribute__((address_space(3)))
; DI void prep_phase(const Args& A, LAS unsigned char* lds, int wv) {
;     ...
;             for (int k = 0; k < 128; ++k) {
;                 const float w = wp[(size_t)k * MOD_LD];
;                 const LAS f32x4* sp = (const LAS f32x4*)(s_lds + k * 20);
;                 const f32x4 s0 = sp[0], s1 = sp[1], s2 = sp[2], s3 = sp[3]; const float s4 = s_lds[k * 20 + 16];
; #pragma unroll
;                 for (int q = 0; q < 4; ++q) { acc[q] += s0[q] * w; acc[4 + q] += s1[q] * w; acc[8 + q] += s2[q] * w; acc[12 + q] += s3[q] * w; }
;                 acc[16] += s4 * w;
	v_pk_fma_f32 v[10:11], v[128:129], v[54:55], v[10:11] op_sel_hi:[0,1,1]
	v_pk_fma_f32 v[8:9], v[128:129], v[56:57], v[8:9] op_sel_hi:[0,1,1]
	s_waitcnt lgkmcnt(9)
	v_pk_fma_f32 v[6:7], v[128:129], v[58:59], v[6:7] op_sel_hi:[0,1,1]
	v_pk_fma_f32 v[4:5], v[128:129], v[60:61], v[4:5] op_sel_hi:[0,1,1]
	v_fmac_f32_e32 v25, v128, v99
	s_waitcnt vmcnt(17) lgkmcnt(8)
	v_pk_fma_f32 v[20:21], v[130:131], v[62:63], v[20:21] op_sel_hi:[0,1,1]
	s_waitcnt lgkmcnt(7)
	v_pk_fma_f32 v[14:15], v[130:131], v[66:67], v[14:15] op_sel_hi:[0,1,1]
	s_waitcnt lgkmcnt(6)
	v_pk_fma_f32 v[10:11], v[130:131], v[70:71], v[10:11] op_sel_hi:[0,1,1]
	s_waitcnt lgkmcnt(5)
	v_pk_fma_f32 v[6:7], v[130:131], v[74:75], v[6:7] op_sel_hi:[0,1,1]
	v_pk_fma_f32 v[18:19], v[130:131], v[64:65], v[18:19] op_sel_hi:[0,1,1]
	v_pk_fma_f32 v[12:13], v[130:131], v[68:69], v[12:13] op_sel_hi:[0,1,1]
	v_pk_fma_f32 v[8:9], v[130:131], v[72:73], v[8:9] op_sel_hi:[0,1,1]
	v_pk_fma_f32 v[4:5], v[130:131], v[76:77], v[4:5] op_sel_hi:[0,1,1]
	s_waitcnt lgkmcnt(4)
	v_fmac_f32_e32 v25, v130, v100
	s_waitcnt vmcnt(16) lgkmcnt(3)
	v_pk_fma_f32 v[20:21], v[132:133], v[78:79], v[20:21] op_sel_hi:[0,1,1]
	s_waitcnt lgkmcnt(2)
	v_pk_fma_f32 v[14:15], v[132:133], v[82:83], v[14:15] op_sel_hi:[0,1,1]
	s_waitcnt lgkmcnt(1)
	v_pk_fma_f32 v[10:11], v[132:133], v[86:87], v[10:11] op_sel_hi:[0,1,1]
	s_waitcnt lgkmcnt(0)
	v_pk_fma_f32 v[6:7], v[132:133], v[90:91], v[6:7] op_sel_hi:[0,1,1]
	v_pk_fma_f32 v[18:19], v[132:133], v[80:81], v[18:19] op_sel_hi:[0,1,1]
	v_pk_fma_f32 v[12:13], v[132:133], v[84:85], v[12:13] op_sel_hi:[0,1,1]
	v_pk_fma_f32 v[8:9], v[132:133], v[88:89], v[8:9] op_sel_hi:[0,1,1]
	v_pk_fma_f32 v[4:5], v[132:133], v[92:93], v[4:5] op_sel_hi:[0,1,1]
	v_fmac_f32_e32 v25, v132, v101
	ds_read_b128 v[26:29], v170
	ds_read_b128 v[34:37], v170 offset:16
	ds_read_b128 v[38:41], v170 offset:32
	ds_read_b128 v[42:45], v170 offset:48
	ds_read2_b32 v[98:99], v170 offset0:16 offset1:36
	ds_read_b128 v[46:49], v170 offset:80
	ds_read_b128 v[50:53], v170 offset:96
	ds_read_b128 v[54:57], v170 offset:112
	ds_read_b128 v[58:61], v170 offset:128
	ds_read_b128 v[62:65], v170 offset:160
	ds_read_b128 v[66:69], v170 offset:176
	ds_read_b128 v[70:73], v170 offset:192
	ds_read_b128 v[74:77], v170 offset:208
	ds_read2_b32 v[100:101], v170 offset0:56 offset1:76
	ds_read_b128 v[78:81], v170 offset:240
	ds_read_b128 v[82:85], v170 offset:256
	ds_read_b128 v[86:89], v170 offset:272
	ds_read_b128 v[90:93], v170 offset:288
	s_waitcnt vmcnt(15) lgkmcnt(14)
	v_pk_fma_f32 v[20:21], v[134:135], v[26:27], v[20:21] op_sel_hi:[0,1,1]
	v_pk_fma_f32 v[18:19], v[134:135], v[28:29], v[18:19] op_sel_hi:[0,1,1]
	v_pk_fma_f32 v[14:15], v[134:135], v[34:35], v[14:15] op_sel_hi:[0,1,1]
	v_pk_fma_f32 v[12:13], v[134:135], v[36:37], v[12:13] op_sel_hi:[0,1,1]
	v_pk_fma_f32 v[10:11], v[134:135], v[38:39], v[10:11] op_sel_hi:[0,1,1]
	v_pk_fma_f32 v[8:9], v[134:135], v[40:41], v[8:9] op_sel_hi:[0,1,1]
	v_pk_fma_f32 v[6:7], v[134:135], v[42:43], v[6:7] op_sel_hi:[0,1,1]
	v_pk_fma_f32 v[4:5], v[134:135], v[44:45], v[4:5] op_sel_hi:[0,1,1]
	s_waitcnt lgkmcnt(13)
	v_fmac_f32_e32 v25, v134, v98
	s_waitcnt vmcnt(14) lgkmcnt(12)
	v_pk_fma_f32 v[20:21], v[136:137], v[46:47], v[20:21] op_sel_hi:[0,1,1]
	v_pk_fma_f32 v[18:19], v[136:137], v[48:49], v[18:19] op_sel_hi:[0,1,1]
	s_waitcnt lgkmcnt(11)
	v_pk_fma_f32 v[14:15], v[136:137], v[50:51], v[14:15] op_sel_hi:[0,1,1]
	v_pk_fma_f32 v[12:13], v[136:137], v[52:53], v[12:13] op_sel_hi:[0,1,1]
	s_waitcnt lgkmcnt(10)
	v_pk_fma_f32 v[10:11], v[136:137], v[54:55], v[10:11] op_sel_hi:[0,1,1]
	v_pk_fma_f32 v[8:9], v[136:137], v[56:57], v[8:9] op_sel_hi:[0,1,1]
	s_waitcnt lgkmcnt(9)
	v_pk_fma_f32 v[6:7], v[136:137], v[58:59], v[6:7] op_sel_hi:[0,1,1]
	v_pk_fma_f32 v[4:5], v[136:137], v[60:61], v[4:5] op_sel_hi:[0,1,1]
	v_fmac_f32_e32 v25, v136, v99
	s_waitcnt vmcnt(13) lgkmcnt(8)
	v_pk_fma_f32 v[20:21], v[138:139], v[62:63], v[20:21] op_sel_hi:[0,1,1]
	s_waitcnt lgkmcnt(7)
	v_pk_fma_f32 v[14:15], v[138:139], v[66:67], v[14:15] op_sel_hi:[0,1,1]
	s_waitcnt lgkmcnt(6)
	v_pk_fma_f32 v[10:11], v[138:139], v[70:71], v[10:11] op_sel_hi:[0,1,1]
	s_waitcnt lgkmcnt(5)
	v_pk_fma_f32 v[6:7], v[138:139], v[74:75], v[6:7] op_sel_hi:[0,1,1]
	v_pk_fma_f32 v[18:19], v[138:139], v[64:65], v[18:19] op_sel_hi:[0,1,1]
	v_pk_fma_f32 v[12:13], v[138:139], v[68:69], v[12:13] op_sel_hi:[0,1,1]
	v_pk_fma_f32 v[8:9], v[138:139], v[72:73], v[8:9] op_sel_hi:[0,1,1]
	v_pk_fma_f32 v[4:5], v[138:139], v[76:77], v[4:5] op_sel_hi:[0,1,1]
	s_waitcnt lgkmcnt(4)
	v_fmac_f32_e32 v25, v138, v100
	s_waitcnt vmcnt(12) lgkmcnt(3)
	v_pk_fma_f32 v[20:21], v[140:141], v[78:79], v[20:21] op_sel_hi:[0,1,1]
	s_waitcnt lgkmcnt(2)
	v_pk_fma_f32 v[14:15], v[140:141], v[82:83], v[14:15] op_sel_hi:[0,1,1]
	s_waitcnt lgkmcnt(1)
	v_pk_fma_f32 v[10:11], v[140:141], v[86:87], v[10:11] op_sel_hi:[0,1,1]
	s_waitcnt lgkmcnt(0)
	v_pk_fma_f32 v[6:7], v[140:141], v[90:91], v[6:7] op_sel_hi:[0,1,1]
	v_pk_fma_f32 v[18:19], v[140:141], v[80:81], v[18:19] op_sel_hi:[0,1,1]
	v_pk_fma_f32 v[12:13], v[140:141], v[84:85], v[12:13] op_sel_hi:[0,1,1]
	v_pk_fma_f32 v[8:9], v[140:141], v[88:89], v[8:9] op_sel_hi:[0,1,1]
	v_pk_fma_f32 v[4:5], v[140:141], v[92:93], v[4:5] op_sel_hi:[0,1,1]
	v_fmac_f32_e32 v25, v140, v101
	ds_read_b128 v[26:29], v171
	ds_read_b128 v[34:37], v171 offset:16
	ds_read_b128 v[38:41], v171 offset:32
	ds_read_b128 v[42:45], v171 offset:48
	ds_read2_b32 v[98:99], v171 offset0:16 offset1:36
	ds_read_b128 v[46:49], v171 offset:80
	ds_read_b128 v[50:53], v171 offset:96
	ds_read_b128 v[54:57], v171 offset:112
	ds_read_b128 v[58:61], v171 offset:128
	ds_read_b128 v[62:65], v171 offset:160
	ds_read_b128 v[66:69], v171 offset:176
	ds_read_b128 v[70:73], v171 offset:192
	ds_read_b128 v[74:77], v171 offset:208
	ds_read2_b32 v[100:101], v171 offset0:56 offset1:76
	ds_read_b128 v[78:81], v171 offset:240
	ds_read_b128 v[82:85], v171 offset:256
	ds_read_b128 v[86:89], v171 offset:272
	ds_read_b128 v[90:93], v171 offset:288
	s_waitcnt vmcnt(11) lgkmcnt(14)
; #define LAS __attribute__((address_space(3)))
; DI void prep_phase(const Args& A, LAS unsigned char* lds, int wv) {
;     ...
;             for (int k = 0; k < 128; ++k) {
;                 const float w = wp[(size_t)k * MOD_LD];
;                 const LAS f32x4* sp = (const LAS f32x4*)(s_lds + k * 20);
;                 const f32x4 s0 = sp[0], s1 = sp[1], s2 = sp[2], s3 = sp[3]; const float s4 = s_lds[k * 20 + 16];
; #pragma unroll
;                 for (int q = 0; q < 4; ++q) { acc[q] += s0[q] * w; acc[4 + q] += s1[q] * w; acc[8 + q] += s2[q] * w; acc[12 + q] += s3[q] * w; }
;                 acc[16] += s4 * w;
	v_pk_fma_f32 v[20:21], v[142:143], v[26:27], v[20:21] op_sel_hi:[0,1,1]
	v_pk_fma_f32 v[18:19], v[142:143], v[28:29], v[18:19] op_sel_hi:[0,1,1]
	v_pk_fma_f32 v[14:15], v[142:143], v[34:35], v[14:15] op_sel_hi:[0,1,1]
	v_pk_fma_f32 v[12:13], v[142:143], v[36:37], v[12:13] op_sel_hi:[0,1,1]
	v_pk_fma_f32 v[10:11], v[142:143], v[38:39], v[10:11] op_sel_hi:[0,1,1]
	v_pk_fma_f32 v[8:9], v[142:143], v[40:41], v[8:9] op_sel_hi:[0,1,1]
	v_pk_fma_f32 v[6:7], v[142:143], v[42:43], v[6:7] op_sel_hi:[0,1,1]
	v_pk_fma_f32 v[4:5], v[142:143], v[44:45], v[4:5] op_sel_hi:[0,1,1]
	s_waitcnt lgkmcnt(13)
	v_fmac_f32_e32 v25, v142, v98
	s_waitcnt vmcnt(10) lgkmcnt(12)
	v_pk_fma_f32 v[20:21], v[144:145], v[46:47], v[20:21] op_sel_hi:[0,1,1]
	v_pk_fma_f32 v[18:19], v[144:145], v[48:49], v[18:19] op_sel_hi:[0,1,1]
	s_waitcnt lgkmcnt(11)
	v_pk_fma_f32 v[14:15], v[144:145], v[50:51], v[14:15] op_sel_hi:[0,1,1]
	v_pk_fma_f32 v[12:13], v[144:145], v[52:53], v[12:13] op_sel_hi:[0,1,1]
	s_waitcnt lgkmcnt(10)
	v_pk_fma_f32 v[10:11], v[144:145], v[54:55], v[10:11] op_sel_hi:[0,1,1]
	v_pk_fma_f32 v[8:9], v[144:145], v[56:57], v[8:9] op_sel_hi:[0,1,1]
	s_waitcnt lgkmcnt(9)
	v_pk_fma_f32 v[6:7], v[144:145], v[58:59], v[6:7] op_sel_hi:[0,1,1]
	v_pk_fma_f32 v[4:5], v[144:145], v[60:61], v[4:5] op_sel_hi:[0,1,1]
	v_fmac_f32_e32 v25, v144, v99
	s_waitcnt vmcnt(9) lgkmcnt(8)
	v_pk_fma_f32 v[20:21], v[146:147], v[62:63], v[20:21] op_sel_hi:[0,1,1]
	s_waitcnt lgkmcnt(7)
	v_pk_fma_f32 v[14:15], v[146:147], v[66:67], v[14:15] op_sel_hi:[0,1,1]
	s_waitcnt lgkmcnt(6)
	v_pk_fma_f32 v[10:11], v[146:147], v[70:71], v[10:11] op_sel_hi:[0,1,1]
	s_waitcnt lgkmcnt(5)
	v_pk_fma_f32 v[6:7], v[146:147], v[74:75], v[6:7] op_sel_hi:[0,1,1]
	v_pk_fma_f32 v[18:19], v[146:147], v[64:65], v[18:19] op_sel_hi:[0,1,1]
	v_pk_fma_f32 v[12:13], v[146:147], v[68:69], v[12:13] op_sel_hi:[0,1,1]
	v_pk_fma_f32 v[8:9], v[146:147], v[72:73], v[8:9] op_sel_hi:[0,1,1]
	v_pk_fma_f32 v[4:5], v[146:147], v[76:77], v[4:5] op_sel_hi:[0,1,1]
	s_waitcnt lgkmcnt(4)
	v_fmac_f32_e32 v25, v146, v100
	s_waitcnt vmcnt(8) lgkmcnt(3)
	v_pk_fma_f32 v[20:21], v[148:149], v[78:79], v[20:21] op_sel_hi:[0,1,1]
	s_waitcnt lgkmcnt(2)
	v_pk_fma_f32 v[14:15], v[148:149], v[82:83], v[14:15] op_sel_hi:[0,1,1]
	s_waitcnt lgkmcnt(1)
	v_pk_fma_f32 v[10:11], v[148:149], v[86:87], v[10:11] op_sel_hi:[0,1,1]
	s_waitcnt lgkmcnt(0)
	v_pk_fma_f32 v[6:7], v[148:149], v[90:91], v[6:7] op_sel_hi:[0,1,1]
	v_pk_fma_f32 v[18:19], v[148:149], v[80:81], v[18:19] op_sel_hi:[0,1,1]
	v_pk_fma_f32 v[12:13], v[148:149], v[84:85], v[12:13] op_sel_hi:[0,1,1]
	v_pk_fma_f32 v[8:9], v[148:149], v[88:89], v[8:9] op_sel_hi:[0,1,1]
	v_pk_fma_f32 v[4:5], v[148:149], v[92:93], v[4:5] op_sel_hi:[0,1,1]
	v_fmac_f32_e32 v25, v148, v101
	ds_read_b128 v[26:29], v172
	ds_read_b128 v[34:37], v172 offset:16
	ds_read_b128 v[38:41], v172 offset:32
	ds_read_b128 v[42:45], v172 offset:48
	ds_read2_b32 v[98:99], v172 offset0:16 offset1:36
	ds_read_b128 v[46:49], v172 offset:80
	ds_read_b128 v[50:53], v172 offset:96
	ds_read_b128 v[54:57], v172 offset:112
	ds_read_b128 v[58:61], v172 offset:128
	ds_read_b128 v[62:65], v172 offset:160
	ds_read_b128 v[66:69], v172 offset:176
	ds_read_b128 v[70:73], v172 offset:192
	ds_read_b128 v[74:77], v172 offset:208
	ds_read2_b32 v[100:101], v172 offset0:56 offset1:76
	ds_read_b128 v[78:81], v172 offset:240
	ds_read_b128 v[82:85], v172 offset:256
	ds_read_b128 v[86:89], v172 offset:272
	ds_read_b128 v[90:93], v172 offset:288
	s_waitcnt vmcnt(7) lgkmcnt(14)
	v_pk_fma_f32 v[20:21], v[150:151], v[26:27], v[20:21] op_sel_hi:[0,1,1]
	v_pk_fma_f32 v[18:19], v[150:151], v[28:29], v[18:19] op_sel_hi:[0,1,1]
	v_pk_fma_f32 v[14:15], v[150:151], v[34:35], v[14:15] op_sel_hi:[0,1,1]
	v_pk_fma_f32 v[12:13], v[150:151], v[36:37], v[12:13] op_sel_hi:[0,1,1]
	v_pk_fma_f32 v[10:11], v[150:151], v[38:39], v[10:11] op_sel_hi:[0,1,1]
	v_pk_fma_f32 v[8:9], v[150:151], v[40:41], v[8:9] op_sel_hi:[0,1,1]
	v_pk_fma_f32 v[6:7], v[150:151], v[42:43], v[6:7] op_sel_hi:[0,1,1]
	v_pk_fma_f32 v[4:5], v[150:151], v[44:45], v[4:5] op_sel_hi:[0,1,1]
	s_waitcnt lgkmcnt(13)
	v_fmac_f32_e32 v25, v150, v98
	s_waitcnt vmcnt(6) lgkmcnt(12)
	v_pk_fma_f32 v[20:21], v[152:153], v[46:47], v[20:21] op_sel_hi:[0,1,1]
	v_pk_fma_f32 v[18:19], v[152:153], v[48:49], v[18:19] op_sel_hi:[0,1,1]
	s_waitcnt lgkmcnt(11)
	v_pk_fma_f32 v[14:15], v[152:153], v[50:51], v[14:15] op_sel_hi:[0,1,1]
	v_pk_fma_f32 v[12:13], v[152:153], v[52:53], v[12:13] op_sel_hi:[0,1,1]
	s_waitcnt lgkmcnt(10)
	v_pk_fma_f32 v[10:11], v[152:153], v[54:55], v[10:11] op_sel_hi:[0,1,1]
	v_pk_fma_f32 v[8:9], v[152:153], v[56:57], v[8:9] op_sel_hi:[0,1,1]
	s_waitcnt lgkmcnt(9)
	v_pk_fma_f32 v[6:7], v[152:153], v[58:59], v[6:7] op_sel_hi:[0,1,1]
	v_pk_fma_f32 v[4:5], v[152:153], v[60:61], v[4:5] op_sel_hi:[0,1,1]
	v_fmac_f32_e32 v25, v152, v99
	s_waitcnt vmcnt(5) lgkmcnt(8)
	v_pk_fma_f32 v[20:21], v[154:155], v[62:63], v[20:21] op_sel_hi:[0,1,1]
	s_waitcnt lgkmcnt(7)
	v_pk_fma_f32 v[14:15], v[154:155], v[66:67], v[14:15] op_sel_hi:[0,1,1]
	s_waitcnt lgkmcnt(6)
; #define LAS __attribute__((address_space(3)))
; DI void prep_phase(const Args& A, LAS unsigned char* lds, int wv) {
;     ...
;             for (int k = 0; k < 128; ++k) {
;                 const float w = wp[(size_t)k * MOD_LD];
;                 const LAS f32x4* sp = (const LAS f32x4*)(s_lds + k * 20);
;                 const f32x4 s0 = sp[0], s1 = sp[1], s2 = sp[2], s3 = sp[3]; const float s4 = s_lds[k * 20 + 16];
; #pragma unroll
;                 for (int q = 0; q < 4; ++q) { acc[q] += s0[q] * w; acc[4 + q] += s1[q] * w; acc[8 + q] += s2[q] * w; acc[12 + q] += s3[q] * w; }
;                 acc[16] += s4 * w;
;             }
;             const float bias = (kc == 0) ? ab[l * MOD_LD + j] : 0.f;
	v_pk_fma_f32 v[10:11], v[154:155], v[70:71], v[10:11] op_sel_hi:[0,1,1]
	s_waitcnt lgkmcnt(5)
	v_pk_fma_f32 v[6:7], v[154:155], v[74:75], v[6:7] op_sel_hi:[0,1,1]
	v_pk_fma_f32 v[18:19], v[154:155], v[64:65], v[18:19] op_sel_hi:[0,1,1]
	v_pk_fma_f32 v[12:13], v[154:155], v[68:69], v[12:13] op_sel_hi:[0,1,1]
	v_pk_fma_f32 v[8:9], v[154:155], v[72:73], v[8:9] op_sel_hi:[0,1,1]
	v_pk_fma_f32 v[4:5], v[154:155], v[76:77], v[4:5] op_sel_hi:[0,1,1]
	s_waitcnt lgkmcnt(4)
	v_fmac_f32_e32 v25, v154, v100
	s_waitcnt vmcnt(4) lgkmcnt(3)
	v_pk_fma_f32 v[20:21], v[156:157], v[78:79], v[20:21] op_sel_hi:[0,1,1]
	s_waitcnt lgkmcnt(2)
	v_pk_fma_f32 v[14:15], v[156:157], v[82:83], v[14:15] op_sel_hi:[0,1,1]
	s_waitcnt lgkmcnt(1)
	v_pk_fma_f32 v[10:11], v[156:157], v[86:87], v[10:11] op_sel_hi:[0,1,1]
	s_waitcnt lgkmcnt(0)
	v_pk_fma_f32 v[6:7], v[156:157], v[90:91], v[6:7] op_sel_hi:[0,1,1]
	v_pk_fma_f32 v[18:19], v[156:157], v[80:81], v[18:19] op_sel_hi:[0,1,1]
	v_pk_fma_f32 v[12:13], v[156:157], v[84:85], v[12:13] op_sel_hi:[0,1,1]
	v_pk_fma_f32 v[8:9], v[156:157], v[88:89], v[8:9] op_sel_hi:[0,1,1]
	v_pk_fma_f32 v[4:5], v[156:157], v[92:93], v[4:5] op_sel_hi:[0,1,1]
	v_fmac_f32_e32 v25, v156, v101
	ds_read_b128 v[26:29], v173
	ds_read_b128 v[34:37], v173 offset:16
	ds_read_b128 v[38:41], v173 offset:32
	ds_read_b128 v[42:45], v173 offset:48
	ds_read2_b32 v[98:99], v173 offset0:16 offset1:36
	ds_read_b128 v[46:49], v173 offset:80
	ds_read_b128 v[50:53], v173 offset:96
	ds_read_b128 v[54:57], v173 offset:112
	ds_read_b128 v[58:61], v173 offset:128
	ds_read_b128 v[62:65], v173 offset:160
	ds_read_b128 v[66:69], v173 offset:176
	ds_read_b128 v[70:73], v173 offset:192
	ds_read_b128 v[74:77], v173 offset:208
	ds_read2_b32 v[100:101], v173 offset0:56 offset1:76
	ds_read_b128 v[78:81], v173 offset:240
	ds_read_b128 v[82:85], v173 offset:256
	ds_read_b128 v[86:89], v173 offset:272
	ds_read_b128 v[90:93], v173 offset:288
	s_waitcnt vmcnt(3) lgkmcnt(14)
	v_pk_fma_f32 v[20:21], v[158:159], v[26:27], v[20:21] op_sel_hi:[0,1,1]
	v_pk_fma_f32 v[18:19], v[158:159], v[28:29], v[18:19] op_sel_hi:[0,1,1]
	v_pk_fma_f32 v[14:15], v[158:159], v[34:35], v[14:15] op_sel_hi:[0,1,1]
	v_pk_fma_f32 v[12:13], v[158:159], v[36:37], v[12:13] op_sel_hi:[0,1,1]
	v_pk_fma_f32 v[10:11], v[158:159], v[38:39], v[10:11] op_sel_hi:[0,1,1]
	v_pk_fma_f32 v[8:9], v[158:159], v[40:41], v[8:9] op_sel_hi:[0,1,1]
	v_pk_fma_f32 v[6:7], v[158:159], v[42:43], v[6:7] op_sel_hi:[0,1,1]
	v_pk_fma_f32 v[4:5], v[158:159], v[44:45], v[4:5] op_sel_hi:[0,1,1]
	s_waitcnt lgkmcnt(13)
	v_fmac_f32_e32 v25, v158, v98
	s_waitcnt vmcnt(2) lgkmcnt(12)
	v_pk_fma_f32 v[20:21], v[160:161], v[46:47], v[20:21] op_sel_hi:[0,1,1]
	v_pk_fma_f32 v[18:19], v[160:161], v[48:49], v[18:19] op_sel_hi:[0,1,1]
	s_waitcnt lgkmcnt(11)
	v_pk_fma_f32 v[14:15], v[160:161], v[50:51], v[14:15] op_sel_hi:[0,1,1]
	v_pk_fma_f32 v[12:13], v[160:161], v[52:53], v[12:13] op_sel_hi:[0,1,1]
	s_waitcnt lgkmcnt(10)
	v_pk_fma_f32 v[10:11], v[160:161], v[54:55], v[10:11] op_sel_hi:[0,1,1]
	v_pk_fma_f32 v[8:9], v[160:161], v[56:57], v[8:9] op_sel_hi:[0,1,1]
	s_waitcnt lgkmcnt(9)
	v_pk_fma_f32 v[6:7], v[160:161], v[58:59], v[6:7] op_sel_hi:[0,1,1]
	v_pk_fma_f32 v[4:5], v[160:161], v[60:61], v[4:5] op_sel_hi:[0,1,1]
	v_fmac_f32_e32 v25, v160, v99
	s_waitcnt vmcnt(1) lgkmcnt(8)
	v_pk_fma_f32 v[20:21], v[162:163], v[62:63], v[20:21] op_sel_hi:[0,1,1]
	s_waitcnt lgkmcnt(7)
	v_pk_fma_f32 v[14:15], v[162:163], v[66:67], v[14:15] op_sel_hi:[0,1,1]
	s_waitcnt lgkmcnt(6)
	v_pk_fma_f32 v[10:11], v[162:163], v[70:71], v[10:11] op_sel_hi:[0,1,1]
	s_waitcnt lgkmcnt(5)
	v_pk_fma_f32 v[6:7], v[162:163], v[74:75], v[6:7] op_sel_hi:[0,1,1]
	v_pk_fma_f32 v[18:19], v[162:163], v[64:65], v[18:19] op_sel_hi:[0,1,1]
	v_pk_fma_f32 v[12:13], v[162:163], v[68:69], v[12:13] op_sel_hi:[0,1,1]
	v_pk_fma_f32 v[8:9], v[162:163], v[72:73], v[8:9] op_sel_hi:[0,1,1]
	v_pk_fma_f32 v[4:5], v[162:163], v[76:77], v[4:5] op_sel_hi:[0,1,1]
	s_waitcnt lgkmcnt(4)
	v_fmac_f32_e32 v25, v162, v100
	s_waitcnt vmcnt(0) lgkmcnt(3)
	v_pk_fma_f32 v[20:21], v[164:165], v[78:79], v[20:21] op_sel_hi:[0,1,1]
	s_waitcnt lgkmcnt(2)
	v_pk_fma_f32 v[14:15], v[164:165], v[82:83], v[14:15] op_sel_hi:[0,1,1]
	s_waitcnt lgkmcnt(1)
	v_pk_fma_f32 v[10:11], v[164:165], v[86:87], v[10:11] op_sel_hi:[0,1,1]
	s_waitcnt lgkmcnt(0)
	v_pk_fma_f32 v[6:7], v[164:165], v[90:91], v[6:7] op_sel_hi:[0,1,1]
	v_pk_fma_f32 v[18:19], v[164:165], v[80:81], v[18:19] op_sel_hi:[0,1,1]
	v_pk_fma_f32 v[12:13], v[164:165], v[84:85], v[12:13] op_sel_hi:[0,1,1]
	v_pk_fma_f32 v[8:9], v[164:165], v[88:89], v[8:9] op_sel_hi:[0,1,1]
	v_pk_fma_f32 v[4:5], v[164:165], v[92:93], v[4:5] op_sel_hi:[0,1,1]
	v_fmac_f32_e32 v25, v164, v101
	s_add_u32 s10, s10, 0xc0000
	s_addc_u32 s11, s11, 0
	s_addk_i32 s9, 0xa00
	s_cmp_eq_u32 s10, 0x300000
	s_cbranch_scc0 .LBB0_12
	s_cmp_eq_u32 s39, 0
	v_mov_b32_e32 v22, 0
	s_cbranch_scc0 .LBB0_7
	s_mul_i32 s4, s8, 0x1800
	v_add_u32_e32 v22, s4, v16
	v_ashrrev_i32_e32 v23, 31, v22
	v_lshl_add_u64 v[22:23], v[22:23], 2, s[22:23]
	global_load_dword v22, v[22:23], off
	s_branch .LBB0_7

; #define SBAR() __builtin_amdgcn_sched_barrier(0)
; #define SWRITE(b, i) do { *(bf16x8*)((char*)V_lds + (b) * SHM_V + vst0) = sr_[i].vs0;          \
;     *(bf16x8*)((char*)V_lds + (b) * SHM_V + vst1) = sr_[i].vs1; int kc = sc * 2;               \
;     *(bf16x8*)((char*)K_lds + (b) * SHM_K + KSWZ(sr, kc)) = sr_[i].ks0;                       \
;     *(bf16x8*)((char*)K_lds + (b) * SHM_K + KSWZ(32 + sr, kc)) = sr_[i].ks1; } while (0)
; #define SWAIT() asm volatile("s_waitcnt vmcnt(4)" ::: "memory")
; #define RESC(a) do { if (__any((a) < 1.f)) { if (hi == 0) al_l[r32] = (a); asm volatile("s_waitcnt lgkmcnt(0)" ::: "memory"); \
;     _Pragma("unroll") for (int d = 0; d < 4; ++d) _Pragma("unroll") for (int r = 0; r < 16; ++r) o[d][r] *= al_l[crow(r, hi)]; } } while (0)
; template <int D0> DI void pv_one(f32x16& od, int vb, bf16x8 pa0, bf16x8 pa1, bf16x8 pa2, bf16x8 pa3) {
;   const s16x4 l0 = tr_read<v_rd_off(D0, 0, 0)>(vb), h0 = tr_read<v_rd_off(D0, 0, 1)>(vb), l1 = tr_read<v_rd_off(D0, 1, 0)>(vb), h1 = tr_read<v_rd_off(D0, 1, 1)>(vb);
;   const s16x4 l2 = tr_read<v_rd_off(D0, 2, 0)>(vb), h2 = tr_read<v_rd_off(D0, 2, 1)>(vb), l3 = tr_read<v_rd_off(D0, 3, 0)>(vb), h3 = tr_read<v_rd_off(D0, 3, 1)>(vb);
;   asm volatile("s_waitcnt lgkmcnt(0)" ::: "memory"); SBAR();
;     ...
;   od = __builtin_amdgcn_mfma_f32_32x32x16_bf16(pa0, PK(l0, h0), od, 0, 0, 0);
;   od = __builtin_amdgcn_mfma_f32_32x32x16_bf16(pa1, PK(l1, h1), od, 0, 0, 0);
;   od = __builtin_amdgcn_mfma_f32_32x32x16_bf16(pa2, PK(l2, h2), od, 0, 0, 0);
;   od = __builtin_amdgcn_mfma_f32_32x32x16_bf16(pa3, PK(l3, h3), od, 0, 0, 0);
; DI void attn_dense_body(const bf16_t* __restrict__ Qb, const bf16_t* __restrict__ Kh, const bf16_t* __restrict__ Vh, const bf16_t* SZb, bf16_t* Ub, int seq, char* lds, int wv, const float* qn, int tpos) {
;     ...
;     pv_d0(o, vb0 + (int)SHM_V, pa0, pa1, pa2, pa3); partialSM(pA0, pA1, m_reg, mnA, alA);
;     __syncthreads(); SWAIT(); SWRITE(1, SO);
;     RESC(alA); __syncthreads();
.LBB0_2007:
	ds_read_b64_tr_b16 v[224:225], v211 offset:0
	ds_read_b64_tr_b16 v[226:227], v211 offset:0x800
	ds_read_b64_tr_b16 v[230:231], v211 offset:0x1000
	ds_read_b64_tr_b16 v[232:233], v211 offset:0x1800
	ds_read_b64_tr_b16 v[234:235], v211 offset:0x2000
	ds_read_b64_tr_b16 v[236:237], v211 offset:0x2800
	ds_read_b64_tr_b16 v[238:239], v211 offset:0x3000
	ds_read_b64_tr_b16 v[240:241], v211 offset:0x3800
	s_waitcnt lgkmcnt(0)
	s_nop 0
	v_mfma_f32_32x32x16_bf16 v[0:15], v[160:163], v[224:227], v[0:15]
	ds_read_b64_tr_b16 v[224:225], v211 offset:0x200
	ds_read_b64_tr_b16 v[226:227], v211 offset:0xa00
	v_mfma_f32_32x32x16_bf16 v[0:15], v[164:167], v[230:233], v[0:15]
	ds_read_b64_tr_b16 v[230:231], v211 offset:0x1200
	ds_read_b64_tr_b16 v[232:233], v211 offset:0x1a00
	v_mfma_f32_32x32x16_bf16 v[0:15], v[168:171], v[234:237], v[0:15]
	ds_read_b64_tr_b16 v[234:235], v211 offset:0x2200
	ds_read_b64_tr_b16 v[236:237], v211 offset:0x2a00
	ds_read_b64_tr_b16 v[242:243], v211 offset:0x3200
	ds_read_b64_tr_b16 v[244:245], v211 offset:0x3a00
	s_waitcnt lgkmcnt(0)
	v_mfma_f32_32x32x16_bf16 v[0:15], v[172:175], v[238:241], v[0:15]
	v_mfma_f32_32x32x16_bf16 v[48:63], v[160:163], v[224:227], v[48:63]
	ds_read_b64_tr_b16 v[224:225], v211 offset:0x400
	ds_read_b64_tr_b16 v[226:227], v211 offset:0xc00
	v_mfma_f32_32x32x16_bf16 v[48:63], v[164:167], v[230:233], v[48:63]
	ds_read_b64_tr_b16 v[230:231], v211 offset:0x1400
	ds_read_b64_tr_b16 v[232:233], v211 offset:0x1c00
	v_mfma_f32_32x32x16_bf16 v[48:63], v[168:171], v[234:237], v[48:63]
	ds_read_b64_tr_b16 v[234:235], v211 offset:0x2400
	ds_read_b64_tr_b16 v[236:237], v211 offset:0x2c00
	ds_read_b64_tr_b16 v[238:239], v211 offset:0x3400
	ds_read_b64_tr_b16 v[240:241], v211 offset:0x3c00
	s_waitcnt lgkmcnt(0)
	v_mfma_f32_32x32x16_bf16 v[48:63], v[172:175], v[242:245], v[48:63]
	v_mfma_f32_32x32x16_bf16 v[32:47], v[160:163], v[224:227], v[32:47]
	ds_read_b64_tr_b16 v[224:225], v211 offset:0x600
	ds_read_b64_tr_b16 v[226:227], v211 offset:0xe00
	v_mfma_f32_32x32x16_bf16 v[32:47], v[164:167], v[230:233], v[32:47]
	ds_read_b64_tr_b16 v[230:231], v211 offset:0x1600
	ds_read_b64_tr_b16 v[232:233], v211 offset:0x1e00
	v_mfma_f32_32x32x16_bf16 v[32:47], v[168:171], v[234:237], v[32:47]
	ds_read_b64_tr_b16 v[234:235], v211 offset:0x2600
	ds_read_b64_tr_b16 v[236:237], v211 offset:0x2e00
	ds_read_b64_tr_b16 v[242:243], v211 offset:0x3600
	ds_read_b64_tr_b16 v[244:245], v211 offset:0x3e00
	s_waitcnt lgkmcnt(0)
	v_mfma_f32_32x32x16_bf16 v[32:47], v[172:175], v[238:241], v[32:47]
	v_mfma_f32_32x32x16_bf16 v[16:31], v[160:163], v[224:227], v[16:31]
	v_max_f32_e32 v219, v81, v81
	v_max_f32_e32 v223, v80, v80
	v_max_f32_e32 v219, v223, v219
	v_max3_f32 v219, v219, v82, v83
	v_max3_f32 v219, v219, v84, v85
	v_max3_f32 v160, v219, v86, v87
	v_max3_f32 v160, v160, v88, v89
	v_max3_f32 v160, v160, v90, v91
	v_mfma_f32_32x32x16_bf16 v[16:31], v[164:167], v[230:233], v[16:31]
	v_max3_f32 v160, v160, v92, v93
	v_max3_f32 v160, v160, v94, v95
	v_max3_f32 v160, v160, v64, v65
	v_max3_f32 v160, v160, v66, v67
	v_max3_f32 v160, v160, v68, v69
	v_max3_f32 v160, v160, v70, v71
	v_max3_f32 v160, v160, v72, v73
	v_max3_f32 v160, v160, v74, v75
	v_mfma_f32_32x32x16_bf16 v[16:31], v[168:171], v[234:237], v[16:31]
	v_max3_f32 v160, v160, v76, v77
	v_max3_f32 v160, v160, v78, v79
	v_mov_b32_e32 v161, v160
	s_nop 1
	v_permlane32_swap_b32_e32 v160, v161
	v_max_f32_e32 v161, v161, v161
	v_max_f32_e32 v160, v160, v160
	v_max_f32_e32 v160, v160, v161
	v_max_f32_e32 v161, v218, v218
	v_max_f32_e32 v161, v161, v160
	v_sub_f32_e32 v162, v160, v218
	v_mfma_f32_32x32x16_bf16 v[16:31], v[172:175], v[242:245], v[16:31]
	v_sub_f32_e32 v160, v218, v161
	v_mul_f32_e32 v160, 0x3e0293ee, v160
	v_exp_f32_e32 v160, v160
	v_cmp_ge_f32_e32 vcc, s28, v162
	s_cmp_eq_u64 vcc, exec
	s_cselect_b64 s[4:5], -1, 0
	s_barrier
	s_waitcnt vmcnt(4)
	v_cndmask_b32_e64 v160, v160, 1.0, s[4:5]
	v_cmp_gt_f32_e32 vcc, 1.0, v160
	s_waitcnt vmcnt(4)
	ds_write_b128 v200, v[144:147] offset:16384
	s_waitcnt vmcnt(4)
	ds_write_b128 v201, v[148:151] offset:16384
	s_waitcnt vmcnt(4)
	ds_write_b128 v202, v[152:155] offset:49152
	s_waitcnt vmcnt(4)
	ds_write_b128 v203, v[156:159] offset:49152
	s_cbranch_vccz .LBB0_2011
	s_and_saveexec_b64 s[12:13], s[0:1]
	ds_write_b32 v207, v160 offset:128
	s_or_b64 exec, exec, s[12:13]
	s_waitcnt lgkmcnt(0)
	v_add_u32_e32 v156, v197, v176
	ds_read_b128 v[144:147], v156 offset:224
	ds_read_b128 v[148:151], v156 offset:192
	ds_read_b128 v[152:155], v156 offset:160
	ds_read_b128 v[156:159], v156 offset:128
	s_waitcnt lgkmcnt(3)
	v_pk_mul_f32 v[12:13], v[12:13], v[144:145]
	s_waitcnt lgkmcnt(2)
	v_pk_mul_f32 v[8:9], v[8:9], v[148:149]
	s_waitcnt lgkmcnt(1)
	v_pk_mul_f32 v[4:5], v[4:5], v[152:153]
	v_pk_mul_f32 v[14:15], v[14:15], v[146:147]
	v_pk_mul_f32 v[10:11], v[10:11], v[150:151]
	v_pk_mul_f32 v[6:7], v[6:7], v[154:155]
	s_waitcnt lgkmcnt(0)
	v_pk_mul_f32 v[2:3], v[2:3], v[158:159]
	v_pk_mul_f32 v[0:1], v[0:1], v[156:157]
	v_pk_mul_f32 v[60:61], v[60:61], v[144:145]
	v_pk_mul_f32 v[56:57], v[56:57], v[148:149]
	v_pk_mul_f32 v[52:53], v[52:53], v[152:153]
	v_pk_mul_f32 v[62:63], v[62:63], v[146:147]
	v_pk_mul_f32 v[58:59], v[58:59], v[150:151]
	v_pk_mul_f32 v[54:55], v[54:55], v[154:155]
	v_pk_mul_f32 v[50:51], v[50:51], v[158:159]
	v_pk_mul_f32 v[48:49], v[48:49], v[156:157]
	v_pk_mul_f32 v[44:45], v[44:45], v[144:145]
	v_pk_mul_f32 v[40:41], v[40:41], v[148:149]
	v_pk_mul_f32 v[36:37], v[36:37], v[152:153]
	v_pk_mul_f32 v[46:47], v[46:47], v[146:147]
	v_pk_mul_f32 v[42:43], v[42:43], v[150:151]
	v_pk_mul_f32 v[38:39], v[38:39], v[154:155]
	v_pk_mul_f32 v[34:35], v[34:35], v[158:159]
	v_pk_mul_f32 v[32:33], v[32:33], v[156:157]
	v_pk_mul_f32 v[28:29], v[28:29], v[144:145]
	v_pk_mul_f32 v[24:25], v[24:25], v[148:149]
	v_pk_mul_f32 v[20:21], v[20:21], v[152:153]
	v_pk_mul_f32 v[30:31], v[30:31], v[146:147]
	v_pk_mul_f32 v[26:27], v[26:27], v[150:151]
	v_pk_mul_f32 v[22:23], v[22:23], v[154:155]
	v_pk_mul_f32 v[18:19], v[18:19], v[158:159]
	v_pk_mul_f32 v[16:17], v[16:17], v[156:157]

; #define SBAR() __builtin_amdgcn_sched_barrier(0)
; #define SLOAD(i, k0) do { sr_[i].vs0 = *reinterpret_cast<const bf16x8*>(&Vh[(long)((k0) + sr) * LDK + sc]); sr_[i].vs1 = *reinterpret_cast<const bf16x8*>(&Vh[(long)((k0) + 32 + sr) * LDK + sc]); \
;     sr_[i].ks0 = *reinterpret_cast<const bf16x8*>(&Kh[(long)((k0) + sr) * LDK + sc]); sr_[i].ks1 = *reinterpret_cast<const bf16x8*>(&Kh[(long)((k0) + 32 + sr) * LDK + sc]); } while (0)
; #define SWRITE(b, i) do { *(bf16x8*)((char*)V_lds + (b) * SHM_V + vst0) = sr_[i].vs0;          \
;     *(bf16x8*)((char*)V_lds + (b) * SHM_V + vst1) = sr_[i].vs1; int kc = sc * 2;               \
;     *(bf16x8*)((char*)K_lds + (b) * SHM_K + KSWZ(sr, kc)) = sr_[i].ks0;                       \
;     *(bf16x8*)((char*)K_lds + (b) * SHM_K + KSWZ(32 + sr, kc)) = sr_[i].ks1; } while (0)
; #define SWAIT() asm volatile("s_waitcnt vmcnt(4)" ::: "memory")
; DI void attn_dense_body(const bf16_t* __restrict__ Qb, const bf16_t* __restrict__ Kh, const bf16_t* __restrict__ Vh, const bf16_t* SZb, bf16_t* Ub, int seq, char* lds, int wv, const float* qn, int tpos) {
;     ...
;     if (j + 3 < NT) SLOAD(SE, (j + 3) * KVBLK); SBAR();
;     pv_d0(o, vb0 + (int)SHM_V, pa0, pa1, pa2, pa3); partialSM(pA0, pA1, m_reg, mnA, alA);
;     __syncthreads(); SWAIT(); SWRITE(1, SO);
.Lattn_skip_ld:
	s_waitcnt vmcnt(0)
	s_branch .LBB0_2007

; #define LAS __attribute__((address_space(3)))
; DI int otid(int wv) { int t; asm volatile("v_mbcnt_lo_u32_b32 %0, -1, 0\n\tv_mbcnt_hi_u32_b32 %0, -1, %0" : "=v"(t)); return wv * 64 + t; }
; __global__ void __launch_bounds__(NTHREADS, 2) fwd_megakernel(Args A) {
;     extern __shared__ __attribute__((aligned(16))) unsigned char lds_raw[];
;     LAS unsigned char* lds = (LAS unsigned char*)lds_raw;
;     cg::grid_group grid = cg::this_grid();
;     const int wv = __builtin_amdgcn_readfirstlane(threadIdx.x >> 6);
;     volatile LAS unsigned* bst = (volatile LAS unsigned*)(lds + 152576);
;     if (otid(wv) < 2) bst[otid(wv)] = 0u;
;     __syncthreads();
;     const XcdBarrier gbar = xcd_barrier_post((unsigned*)(A.ws + WS_BAR), bst, wv);
	.amdhsa_kernel _Z14fwd_megakernel4Args
		.amdhsa_group_segment_fixed_size 0
		.amdhsa_private_segment_fixed_size 0
		.amdhsa_kernarg_size 424
		.amdhsa_user_sgpr_count 2
		.amdhsa_user_sgpr_dispatch_ptr 0
		.amdhsa_user_sgpr_queue_ptr 0
		.amdhsa_user_sgpr_kernarg_segment_ptr 1
		.amdhsa_user_sgpr_dispatch_id 0
		.amdhsa_user_sgpr_kernarg_preload_length 0
		.amdhsa_user_sgpr_kernarg_preload_offset 0
		.amdhsa_user_sgpr_private_segment_size 0
		.amdhsa_uses_dynamic_stack 0
		.amdhsa_enable_private_segment 0
		.amdhsa_system_sgpr_workgroup_id_x 1
		.amdhsa_system_sgpr_workgroup_id_y 0
		.amdhsa_system_sgpr_workgroup_id_z 0
		.amdhsa_system_sgpr_workgroup_info 0
		.amdhsa_system_vgpr_workitem_id 2
		.amdhsa_next_free_vgpr 248
		.amdhsa_next_free_sgpr 102
		.amdhsa_accum_offset 248
		.amdhsa_reserve_vcc 1
		.amdhsa_float_round_mode_32 0
		.amdhsa_float_round_mode_16_64 0
		.amdhsa_float_denorm_mode_32 3
		.amdhsa_float_denorm_mode_16_64 3
		.amdhsa_dx10_clamp 1
		.amdhsa_ieee_mode 1
		.amdhsa_fp16_overflow 0
		.amdhsa_tg_split 0
		.amdhsa_exception_fp_ieee_invalid_op 0
		.amdhsa_exception_fp_denorm_src 0
		.amdhsa_exception_fp_ieee_div_zero 0
		.amdhsa_exception_fp_ieee_overflow 0
		.amdhsa_exception_fp_ieee_underflow 0
		.amdhsa_exception_fp_ieee_inexact 0
		.amdhsa_exception_int_div_zero 0
	.end_amdhsa_kernel

; #define LAS __attribute__((address_space(3)))
; DI int otid(int wv) { int t; asm volatile("v_mbcnt_lo_u32_b32 %0, -1, 0\n\tv_mbcnt_hi_u32_b32 %0, -1, %0" : "=v"(t)); return wv * 64 + t; }
; __global__ void __launch_bounds__(NTHREADS, 2) fwd_megakernel(Args A) {
;     extern __shared__ __attribute__((aligned(16))) unsigned char lds_raw[];
;     LAS unsigned char* lds = (LAS unsigned char*)lds_raw;
;     cg::grid_group grid = cg::this_grid();
;     const int wv = __builtin_amdgcn_readfirstlane(threadIdx.x >> 6);
;     volatile LAS unsigned* bst = (volatile LAS unsigned*)(lds + 152576);
;     if (otid(wv) < 2) bst[otid(wv)] = 0u;
;     __syncthreads();
;     const XcdBarrier gbar = xcd_barrier_post((unsigned*)(A.ws + WS_BAR), bst, wv);
amdhsa.kernels:
  - .agpr_count:     0
    .args:
      - .offset:         0
        .size:           168
        .value_kind:     by_value
      - .offset:         168
        .size:           4
        .value_kind:     hidden_block_count_x
      - .offset:         172
        .size:           4
        .value_kind:     hidden_block_count_y
      - .offset:         176
        .size:           4
        .value_kind:     hidden_block_count_z
      - .offset:         180
        .size:           2
        .value_kind:     hidden_group_size_x
      - .offset:         182
        .size:           2
        .value_kind:     hidden_group_size_y
      - .offset:         184
        .size:           2
        .value_kind:     hidden_group_size_z
      - .offset:         186
        .size:           2
        .value_kind:     hidden_remainder_x
      - .offset:         188
        .size:           2
        .value_kind:     hidden_remainder_y
      - .offset:         190
        .size:           2
        .value_kind:     hidden_remainder_z
      - .offset:         208
        .size:           8
        .value_kind:     hidden_global_offset_x
      - .offset:         216
        .size:           8
        .value_kind:     hidden_global_offset_y
      - .offset:         224
        .size:           8
        .value_kind:     hidden_global_offset_z
      - .offset:         232
        .size:           2
        .value_kind:     hidden_grid_dims
      - .offset:         256
        .size:           8
        .value_kind:     hidden_multigrid_sync_arg
      - .offset:         288
        .size:           4
        .value_kind:     hidden_dynamic_lds_size
    .group_segment_fixed_size: 0
    .kernarg_segment_align: 8
    .kernarg_segment_size: 424
    .language:       OpenCL C
    .language_version:
      - 2
      - 0
    .max_flat_workgroup_size: 512
    .name:           _Z14fwd_megakernel4Args
    .private_segment_fixed_size: 0
    .sgpr_count:     108
    .sgpr_spill_count: 71
    .symbol:         _Z14fwd_megakernel4Args.kd
    .uniform_work_group_size: 1
    .uses_dynamic_stack: false
    .vgpr_count:     248
    .vgpr_spill_count: 0
    .wavefront_size: 64
